# direct HBM->LDS: FFN-up row statistics (ssq partials) staged by LDS-DMA from the leading wave-half during the last K iteration into 16 KB of added static LDS, read back with ds_read in the epilogue
# baseline (speedup 1.0000x reference)
; #define PG8_STAGE(bufoff, gbase, voff) do { _Pragma("unroll") for (int _i = 0; _i < 2; ++_i) { \
;         const unsigned _m0 = ldsu + (unsigned)(bufoff) + ldsw + (unsigned)(_i * 8192); \
;         asm volatile("s_mov_b32 m0, %2\n\ts_nop 0\n\tglobal_load_lds_dwordx4 %0, %1" :: "v"((voff)[_i]), "s"((const char*)(gbase)), "s"(_m0) : "memory"); } } while (0)
; #define PG8_LDA(dst, b, h) do { _Pragma("unroll") for (int m = 0; m < 4; ++m) _Pragma("unroll") for (int k = 0; k < 2; ++k) dst[m][k] = *(const LAS bf16x8*)(lds + PG8_SA(b, h) + aoff + m * 2048 + k * 1024); } while (0)
; #define PG8_LDB(dst, b, h) do { _Pragma("unroll") for (int n = 0; n < 2; ++n) _Pragma("unroll") for (int k = 0; k < 2; ++k) dst[n][k] = *(const LAS bf16x8*)(lds + bbase[b][h] + n * 2048 + k * 1024); } while (0)
; #define PG8_WAIT_V(n) asm volatile("s_waitcnt vmcnt(" #n ")" ::: "memory")
; #define PG8_WAIT_L(n) asm volatile("s_waitcnt lgkmcnt(" #n ")" ::: "memory")
; #define PG8_BAR __builtin_amdgcn_s_barrier()
; #define PG8_SCHED __builtin_amdgcn_sched_barrier(0)
; template <class Epi>
; __device__ __forceinline__ void gemm_phase(LAS unsigned char* lds, const Gemm g, const StaticOrder& S, const Epi& E) {
;     ...
;         for (int t = 0; t < nt; t += 2) {
;             const bool last = (t == nt - 2);
;             const char* a2 = last ? nA : cA + (size_t)(t + 2) * kstep; const char* b2 = last ? nB : cB + (size_t)(t + 2) * kstep;
;             const char* a3 = a2 + kstep; const char* b3 = b2 + kstep;
;             const char* b1 = cB + (size_t)(t + 1) * kstep;
;             PG8_LDB(B0, 0, 0); PG8_SCHED; PG8_LDA(At, 0, 0); PG8_LDA(At2, 0, 1); PG8_STAGE(PG8_SB(1, 1), b1 + hstepB, voffB);
;             PG8_WAIT_V(8); PG8_WAIT_L(0); PG8_BAR; PG8_MMA2B(0, At, At2, B0); PG8_BAR; PG8_SCHED;
;             PG8_LDB(B0, 0, 1); PG8_STAGE(PG8_SB(0, 0), b2, voffB); PG8_STAGE(PG8_SA(0, 0), a2, voffA); PG8_STAGE(PG8_SA(0, 1), a2 + hstepA, voffA);
;             PG8_WAIT_V(8); PG8_WAIT_L(0); PG8_BAR; PG8_MMA2B(1, At, At2, B0); PG8_BAR; PG8_SCHED;
.LBB0_1027:
	ds_read_b128 v[68:71], v220
	ds_read_b128 v[84:87], v220 offset:1024
	ds_read_b128 v[88:91], v220 offset:2048
	ds_read_b128 v[92:95], v220 offset:3072
	s_add_u32 s12, s10, 0x100
	s_addc_u32 s13, s11, 0
	s_cmp_eq_u32 s69, 12
	s_cselect_b32 s14, s97, vcc_hi
	s_cselect_b32 s15, s7, s68
	s_cselect_b32 s84, vcc_lo, s12
	s_cselect_b32 s85, s39, s13
	s_add_u32 s16, s14, 0x80
	s_addc_u32 s17, s15, 0
	ds_read_b128 v[96:99], v221
	ds_read_b128 v[100:103], v221 offset:1024
	ds_read_b128 v[152:155], v221 offset:2048
	ds_read_b128 v[156:159], v221 offset:3072
	ds_read_b128 v[166:169], v221 offset:4096
	ds_read_b128 v[178:181], v221 offset:5120
	ds_read_b128 v[182:185], v221 offset:6144
	ds_read_b128 v[186:189], v221 offset:7168
	ds_read_b128 v[190:193], v221 offset:16384
	ds_read_b128 v[194:197], v221 offset:17408
	ds_read_b128 v[198:201], v221 offset:18432
	ds_read_b128 v[202:205], v221 offset:19456
	ds_read_b128 v[226:229], v221 offset:20480
	ds_read_b128 v[230:233], v221 offset:21504
	ds_read_b128 v[234:237], v221 offset:22528
	ds_read_b128 v[238:241], v221 offset:23552
	s_add_u32 s10, s10, 0x40080
	s_addc_u32 s11, s11, 0
	s_mov_b32 m0, s58
	s_nop 0
	global_load_lds_dwordx4 v217, s[10:11]
	s_mov_b32 m0, s60
	s_nop 0
	global_load_lds_dwordx4 v219, s[10:11]
	s_waitcnt vmcnt(8)
	s_waitcnt lgkmcnt(0)
	s_barrier
	v_mfma_f32_16x16x32_bf16 v[80:83], v[68:71], v[96:99], v[80:83]
	v_mfma_f32_16x16x32_bf16 v[76:79], v[88:91], v[96:99], v[76:79]
	v_mfma_f32_16x16x32_bf16 v[148:151], v[68:71], v[152:155], v[148:151]
	v_mfma_f32_16x16x32_bf16 v[52:55], v[88:91], v[152:155], v[52:55]
	v_mfma_f32_16x16x32_bf16 v[144:147], v[68:71], v[166:169], v[144:147]
	v_mfma_f32_16x16x32_bf16 v[48:51], v[88:91], v[166:169], v[48:51]
	v_mfma_f32_16x16x32_bf16 v[136:139], v[68:71], v[182:185], v[136:139]
	v_mfma_f32_16x16x32_bf16 v[40:43], v[88:91], v[182:185], v[40:43]
	v_mfma_f32_16x16x32_bf16 v[124:127], v[68:71], v[190:193], v[124:127]
	v_mfma_f32_16x16x32_bf16 v[28:31], v[88:91], v[190:193], v[28:31]
	v_mfma_f32_16x16x32_bf16 v[120:123], v[68:71], v[198:201], v[120:123]
	v_mfma_f32_16x16x32_bf16 v[24:27], v[88:91], v[198:201], v[24:27]
	v_mfma_f32_16x16x32_bf16 v[112:115], v[68:71], v[226:229], v[112:115]
	v_mfma_f32_16x16x32_bf16 v[16:19], v[88:91], v[226:229], v[16:19]
	v_mfma_f32_16x16x32_bf16 v[64:67], v[68:71], v[234:237], v[64:67]
	v_mfma_f32_16x16x32_bf16 v[4:7], v[88:91], v[234:237], v[4:7]
	v_mfma_f32_16x16x32_bf16 v[80:83], v[84:87], v[100:103], v[80:83]
	v_mfma_f32_16x16x32_bf16 v[76:79], v[92:95], v[100:103], v[76:79]
	v_mfma_f32_16x16x32_bf16 v[148:151], v[84:87], v[156:159], v[148:151]
	v_mfma_f32_16x16x32_bf16 v[52:55], v[92:95], v[156:159], v[52:55]
	v_mfma_f32_16x16x32_bf16 v[144:147], v[84:87], v[178:181], v[144:147]
	v_mfma_f32_16x16x32_bf16 v[48:51], v[92:95], v[178:181], v[48:51]
	v_mfma_f32_16x16x32_bf16 v[136:139], v[84:87], v[186:189], v[136:139]
	v_mfma_f32_16x16x32_bf16 v[40:43], v[92:95], v[186:189], v[40:43]
	v_mfma_f32_16x16x32_bf16 v[124:127], v[84:87], v[194:197], v[124:127]
	v_mfma_f32_16x16x32_bf16 v[28:31], v[92:95], v[194:197], v[28:31]
	v_mfma_f32_16x16x32_bf16 v[120:123], v[84:87], v[202:205], v[120:123]
	v_mfma_f32_16x16x32_bf16 v[24:27], v[92:95], v[202:205], v[24:27]
	v_mfma_f32_16x16x32_bf16 v[112:115], v[84:87], v[230:233], v[112:115]
	v_mfma_f32_16x16x32_bf16 v[16:19], v[92:95], v[230:233], v[16:19]
	v_mfma_f32_16x16x32_bf16 v[64:67], v[84:87], v[238:241], v[64:67]
	v_mfma_f32_16x16x32_bf16 v[4:7], v[92:95], v[238:241], v[4:7]
	s_barrier
	ds_read_b128 v[68:71], v222
	ds_read_b128 v[84:87], v222 offset:1024
	ds_read_b128 v[88:91], v222 offset:2048
	ds_read_b128 v[92:95], v222 offset:3072
	s_mov_b32 m0, s48
	s_nop 0
	global_load_lds_dwordx4 v217, s[84:85]
	s_mov_b32 m0, s49
	s_nop 0
	global_load_lds_dwordx4 v219, s[84:85]
	s_mov_b32 m0, s47
	s_nop 0
	global_load_lds_dwordx4 v216, s[14:15]
	s_mov_b32 m0, s50
	s_nop 0
	global_load_lds_dwordx4 v218, s[14:15]
	s_add_u32 s10, s14, 0x40000
	s_addc_u32 s11, s15, 0
	s_mov_b32 m0, s51
	s_nop 0
	global_load_lds_dwordx4 v216, s[10:11]
	s_mov_b32 m0, s52
	s_nop 0
	global_load_lds_dwordx4 v218, s[10:11]
	s_waitcnt vmcnt(8)
	s_waitcnt lgkmcnt(0)
	s_barrier
	v_mfma_f32_16x16x32_bf16 v[72:75], v[68:71], v[96:99], v[72:75]
	v_mfma_f32_16x16x32_bf16 v[56:59], v[88:91], v[96:99], v[56:59]
	v_mfma_f32_16x16x32_bf16 v[44:47], v[88:91], v[152:155], v[44:47]
	v_mfma_f32_16x16x32_bf16 v[36:39], v[88:91], v[166:169], v[36:39]
	v_mfma_f32_16x16x32_bf16 v[128:131], v[68:71], v[182:185], v[128:131]
	v_mfma_f32_16x16x32_bf16 v[32:35], v[88:91], v[182:185], v[32:35]
	v_mfma_f32_16x16x32_bf16 v[116:119], v[68:71], v[190:193], v[116:119]
	v_mfma_f32_16x16x32_bf16 v[20:23], v[88:91], v[190:193], v[20:23]
	v_mfma_f32_16x16x32_bf16 v[108:111], v[68:71], v[198:201], v[108:111]
	v_mfma_f32_16x16x32_bf16 v[12:15], v[88:91], v[198:201], v[12:15]
	v_mfma_f32_16x16x32_bf16 v[104:107], v[68:71], v[226:229], v[104:107]
	v_mfma_f32_16x16x32_bf16 v[8:11], v[88:91], v[226:229], v[8:11]
	v_mfma_f32_16x16x32_bf16 v[60:63], v[68:71], v[234:237], v[60:63]
	v_mfma_f32_16x16x32_bf16 v[0:3], v[88:91], v[234:237], v[0:3]
	v_mfma_f32_16x16x32_bf16 v[72:75], v[84:87], v[100:103], v[72:75]
	v_mfma_f32_16x16x32_bf16 v[56:59], v[92:95], v[100:103], v[56:59]
	v_mfma_f32_16x16x32_bf16 v[96:99], v[68:71], v[152:155], v[140:143]
	v_mfma_f32_16x16x32_bf16 v[44:47], v[92:95], v[156:159], v[44:47]
	v_mfma_f32_16x16x32_bf16 v[100:103], v[68:71], v[166:169], v[132:135]
	v_mfma_f32_16x16x32_bf16 v[36:39], v[92:95], v[178:181], v[36:39]
	v_mfma_f32_16x16x32_bf16 v[128:131], v[84:87], v[186:189], v[128:131]
	v_mfma_f32_16x16x32_bf16 v[32:35], v[92:95], v[186:189], v[32:35]
	v_mfma_f32_16x16x32_bf16 v[116:119], v[84:87], v[194:197], v[116:119]
	v_mfma_f32_16x16x32_bf16 v[20:23], v[92:95], v[194:197], v[20:23]
	v_mfma_f32_16x16x32_bf16 v[108:111], v[84:87], v[202:205], v[108:111]
	v_mfma_f32_16x16x32_bf16 v[12:15], v[92:95], v[202:205], v[12:15]
	v_mfma_f32_16x16x32_bf16 v[104:107], v[84:87], v[230:233], v[104:107]
	v_mfma_f32_16x16x32_bf16 v[8:11], v[92:95], v[230:233], v[8:11]
	v_mfma_f32_16x16x32_bf16 v[60:63], v[84:87], v[238:241], v[60:63]
	v_mfma_f32_16x16x32_bf16 v[0:3], v[92:95], v[238:241], v[0:3]
	v_mfma_f32_16x16x32_bf16 v[96:99], v[84:87], v[156:159], v[96:99]
	v_mfma_f32_16x16x32_bf16 v[100:103], v[84:87], v[178:181], v[100:103]
	s_barrier
; #define LAS __attribute__((address_space(3)))
; #define PG8_STAGE(bufoff, gbase, voff) do { _Pragma("unroll") for (int _i = 0; _i < 2; ++_i) { \
;         const unsigned _m0 = ldsu + (unsigned)(bufoff) + ldsw + (unsigned)(_i * 8192); \
;         asm volatile("s_mov_b32 m0, %2\n\ts_nop 0\n\tglobal_load_lds_dwordx4 %0, %1" :: "v"((voff)[_i]), "s"((const char*)(gbase)), "s"(_m0) : "memory"); } } while (0)
; #define PG8_LDA(dst, b, h) do { _Pragma("unroll") for (int m = 0; m < 4; ++m) _Pragma("unroll") for (int k = 0; k < 2; ++k) dst[m][k] = *(const LAS bf16x8*)(lds + PG8_SA(b, h) + aoff + m * 2048 + k * 1024); } while (0)
; #define PG8_LDB(dst, b, h) do { _Pragma("unroll") for (int n = 0; n < 2; ++n) _Pragma("unroll") for (int k = 0; k < 2; ++k) dst[n][k] = *(const LAS bf16x8*)(lds + bbase[b][h] + n * 2048 + k * 1024); } while (0)
; #define PG8_WAIT_V(n) asm volatile("s_waitcnt vmcnt(" #n ")" ::: "memory")
; #define PG8_WAIT_L(n) asm volatile("s_waitcnt lgkmcnt(" #n ")" ::: "memory")
; #define PG8_BAR __builtin_amdgcn_s_barrier()
; #define PG8_SCHED __builtin_amdgcn_sched_barrier(0)
; template <class Epi>
; __device__ __forceinline__ void gemm_phase(LAS unsigned char* lds, const Gemm g, const StaticOrder& S, const Epi& E) {
;     ...
;             PG8_LDB(B0, 1, 0); PG8_SCHED; PG8_LDA(At, 1, 0); PG8_LDA(At2, 1, 1); PG8_STAGE(PG8_SB(0, 1), b2 + hstepB, voffB);
;             PG8_WAIT_V(8); PG8_WAIT_L(0); PG8_BAR; PG8_MMA2B(0, At, At2, B0); PG8_BAR; PG8_SCHED;
;             PG8_LDB(B0, 1, 1); PG8_STAGE(PG8_SB(1, 0), b3, voffB); PG8_STAGE(PG8_SA(1, 0), a3, voffA); PG8_STAGE(PG8_SA(1, 1), a3 + hstepA, voffA);
;     __device__ __forceinline__ void operator()(f32x4 (&acc)[2][2][4][2], const Unit& u, int wr, int wc, int fr, int fq) const {
;     ...
;           else { const int which = t >> 6, j = (t & 63) * 4, bj = j >> 7, c = j & 127; const float* src = (which < 3 ? cw + (size_t)which * NUP : cb) + bj * DFF + u.pn * 128 + c;
;               *(LAS f32x4*)(cwL + which * 256 + j) = *(const f32x4*)src; } }
	ds_read_b128 v[68:71], v223
	ds_read_b128 v[84:87], v223 offset:1024
	ds_read_b128 v[88:91], v223 offset:2048
	ds_read_b128 v[92:95], v223 offset:3072
	ds_read_b128 v[132:135], v221 offset:32768
	ds_read_b128 v[140:143], v221 offset:33792
	ds_read_b128 v[152:155], v221 offset:34816
	ds_read_b128 v[156:159], v221 offset:35840
	ds_read_b128 v[166:169], v221 offset:36864
	ds_read_b128 v[178:181], v221 offset:37888
	ds_read_b128 v[182:185], v221 offset:38912
	ds_read_b128 v[186:189], v221 offset:39936
	ds_read_b128 v[190:193], v221 offset:49152
	ds_read_b128 v[194:197], v221 offset:50176
	ds_read_b128 v[198:201], v221 offset:51200
	ds_read_b128 v[202:205], v221 offset:52224
	ds_read_b128 v[226:229], v221 offset:53248
	ds_read_b128 v[230:233], v221 offset:54272
	ds_read_b128 v[234:237], v221 offset:55296
	ds_read_b128 v[238:241], v221 offset:56320
	s_add_u32 s10, s84, 0x40000
	s_addc_u32 s11, s85, 0
	s_mov_b32 m0, s53
	s_nop 0
	global_load_lds_dwordx4 v217, s[10:11]
	s_mov_b32 m0, s54
	s_nop 0
	global_load_lds_dwordx4 v219, s[10:11]
	s_waitcnt vmcnt(8)
	s_waitcnt lgkmcnt(0)
	s_barrier
	v_mfma_f32_16x16x32_bf16 v[80:83], v[68:71], v[132:135], v[80:83]
	v_mfma_f32_16x16x32_bf16 v[76:79], v[88:91], v[132:135], v[76:79]
	v_mfma_f32_16x16x32_bf16 v[148:151], v[68:71], v[152:155], v[148:151]
	v_mfma_f32_16x16x32_bf16 v[52:55], v[88:91], v[152:155], v[52:55]
	v_mfma_f32_16x16x32_bf16 v[144:147], v[68:71], v[166:169], v[144:147]
	v_mfma_f32_16x16x32_bf16 v[48:51], v[88:91], v[166:169], v[48:51]
	v_mfma_f32_16x16x32_bf16 v[136:139], v[68:71], v[182:185], v[136:139]
	v_mfma_f32_16x16x32_bf16 v[40:43], v[88:91], v[182:185], v[40:43]
	v_mfma_f32_16x16x32_bf16 v[124:127], v[68:71], v[190:193], v[124:127]
	v_mfma_f32_16x16x32_bf16 v[28:31], v[88:91], v[190:193], v[28:31]
	v_mfma_f32_16x16x32_bf16 v[120:123], v[68:71], v[198:201], v[120:123]
	v_mfma_f32_16x16x32_bf16 v[24:27], v[88:91], v[198:201], v[24:27]
	v_mfma_f32_16x16x32_bf16 v[112:115], v[68:71], v[226:229], v[112:115]
	v_mfma_f32_16x16x32_bf16 v[16:19], v[88:91], v[226:229], v[16:19]
	v_mfma_f32_16x16x32_bf16 v[64:67], v[68:71], v[234:237], v[64:67]
	v_mfma_f32_16x16x32_bf16 v[4:7], v[88:91], v[234:237], v[4:7]
	v_mfma_f32_16x16x32_bf16 v[80:83], v[84:87], v[140:143], v[80:83]
	v_mfma_f32_16x16x32_bf16 v[76:79], v[92:95], v[140:143], v[76:79]
	v_mfma_f32_16x16x32_bf16 v[148:151], v[84:87], v[156:159], v[148:151]
	v_mfma_f32_16x16x32_bf16 v[52:55], v[92:95], v[156:159], v[52:55]
	v_mfma_f32_16x16x32_bf16 v[144:147], v[84:87], v[178:181], v[144:147]
	v_mfma_f32_16x16x32_bf16 v[48:51], v[92:95], v[178:181], v[48:51]
	v_mfma_f32_16x16x32_bf16 v[136:139], v[84:87], v[186:189], v[136:139]
	v_mfma_f32_16x16x32_bf16 v[40:43], v[92:95], v[186:189], v[40:43]
	v_mfma_f32_16x16x32_bf16 v[124:127], v[84:87], v[194:197], v[124:127]
	v_mfma_f32_16x16x32_bf16 v[28:31], v[92:95], v[194:197], v[28:31]
	v_mfma_f32_16x16x32_bf16 v[120:123], v[84:87], v[202:205], v[120:123]
	v_mfma_f32_16x16x32_bf16 v[24:27], v[92:95], v[202:205], v[24:27]
	v_mfma_f32_16x16x32_bf16 v[112:115], v[84:87], v[230:233], v[112:115]
	v_mfma_f32_16x16x32_bf16 v[16:19], v[92:95], v[230:233], v[16:19]
	v_mfma_f32_16x16x32_bf16 v[64:67], v[84:87], v[238:241], v[64:67]
	v_mfma_f32_16x16x32_bf16 v[4:7], v[92:95], v[238:241], v[4:7]
	s_barrier
	s_add_u32 s10, s84, 0x80
	ds_read_b128 v[68:71], v224
	ds_read_b128 v[84:87], v224 offset:1024
	ds_read_b128 v[88:91], v224 offset:2048
	ds_read_b128 v[92:95], v224 offset:3072
	s_addc_u32 s11, s85, 0
	s_mov_b32 m0, s88
	s_nop 0
	global_load_lds_dwordx4 v217, s[10:11]
	s_mov_b32 m0, s89
	s_nop 0
	global_load_lds_dwordx4 v219, s[10:11]
	s_mov_b32 m0, s95
	s_nop 0
	global_load_lds_dwordx4 v216, s[16:17]
	s_mov_b32 m0, s37
	s_nop 0
	global_load_lds_dwordx4 v218, s[16:17]
	s_add_u32 s10, s14, 0x40080
	s_addc_u32 s11, s15, 0
	s_mov_b32 m0, s56
	s_nop 0
	global_load_lds_dwordx4 v216, s[10:11]
	s_mov_b32 m0, s57
	s_nop 0
	global_load_lds_dwordx4 v218, s[10:11]
	s_cmp_eq_u32 s69, 12
	s_cbranch_scc0 .Lcw_skip
	s_cmp_eq_u64 s[4:5], 0
	s_cbranch_scc1 .Lssq_dma
	v_lshlrev_b32_e32 v242, 4, v215
	v_add3_u32 v242, v214, s59, v242
	s_lshr_b32 s32, s59, 6
	s_mul_i32 s98, s32, 0x5800
	s_add_u32 s98, s0, s98
	s_addc_u32 s99, s1, 0
	s_cmp_lt_u32 s32, 3
	s_cselect_b32 s98, s98, s2
	s_cselect_b32 s99, s99, s3
	s_lshl_b32 s32, s67, 9
	s_add_u32 s98, s98, s32
	s_addc_u32 s99, s99, 0
	v_bfe_u32 v243, v242, 5, 1
	v_mul_u32_u24_e32 v243, 0x2c00, v243
	v_and_b32_e32 v244, 31, v242
	v_lshl_add_u32 v243, v244, 4, v243
	v_readlane_b32 s32, v252, 44
	s_nop 3
	s_lshl_b32 m0, s59, 4
	s_add_u32 m0, m0, s32
	s_nop 0
	global_load_lds_dwordx4 v243, s[98:99]
	s_branch .Lcw_skip
; #define PG8_WAIT_V(n) asm volatile("s_waitcnt vmcnt(" #n ")" ::: "memory")
; #define PG8_WAIT_L(n) asm volatile("s_waitcnt lgkmcnt(" #n ")" ::: "memory")
; #define PG8_BAR __builtin_amdgcn_s_barrier()
; #define PG8_SCHED __builtin_amdgcn_sched_barrier(0)
; template <class Epi>
; __device__ __forceinline__ void gemm_phase(LAS unsigned char* lds, const Gemm g, const StaticOrder& S, const Epi& E) {
;     ...
;             PG8_WAIT_V(8); PG8_WAIT_L(0); PG8_BAR; PG8_MMA2B(1, At, At2, B0); PG8_BAR; PG8_SCHED;
;         }
;         if (wr == 0) PG8_BAR;
;     __device__ __forceinline__ void operator()(f32x4 (&acc)[2][2][4][2], const Unit& u, int wr, int wc, int fr, int fq) const {
;     ...
;           if (wr == 0) { const float* sp = ssq + ((size_t)u.pm * 256 + t) * 16; const f32x4 a = *(const f32x4*)sp, b = *(const f32x4*)(sp + 4), c = *(const f32x4*)(sp + 8), d = *(const f32x4*)(sp + 12);
;               const f32x4 q = (a + b) + (c + d); rsL[t] = rsqrtf(((q[0] + q[1]) + (q[2] + q[3])) * (1.0f / 1024.0f) + EPS); }
.Lssq_dma:
	v_lshlrev_b32_e32 v242, 4, v215
	v_add3_u32 v242, v214, s59, v242
	v_lshlrev_b32_e32 v242, 6, v242
	s_lshl_b32 s32, s96, 14
	s_add_u32 s98, s18, s32
	s_addc_u32 s99, s19, 0
	s_lshl_b32 s32, s59, 6
	s_add_u32 s32, s32, 0x23440
	s_mov_b32 m0, s32
	s_nop 0
	global_load_lds_dwordx4 v242, s[98:99]
	s_add_u32 m0, s32, 0x3f0
	s_nop 0
	global_load_lds_dwordx4 v242, s[98:99] offset:16
	s_add_u32 m0, s32, 0x7e0
	s_nop 0
	global_load_lds_dwordx4 v242, s[98:99] offset:32
	s_add_u32 m0, s32, 0xbd0
	s_nop 0
	global_load_lds_dwordx4 v242, s[98:99] offset:48
.Lcw_skip:
	s_waitcnt vmcnt(8)
	s_waitcnt lgkmcnt(0)
	s_barrier
	v_mfma_f32_16x16x32_bf16 v[72:75], v[68:71], v[132:135], v[72:75]
	v_mfma_f32_16x16x32_bf16 v[56:59], v[88:91], v[132:135], v[56:59]
	v_mfma_f32_16x16x32_bf16 v[96:99], v[68:71], v[152:155], v[96:99]
	v_mfma_f32_16x16x32_bf16 v[72:75], v[84:87], v[140:143], v[72:75]
	v_mfma_f32_16x16x32_bf16 v[56:59], v[92:95], v[140:143], v[56:59]
	v_mfma_f32_16x16x32_bf16 v[140:143], v[84:87], v[156:159], v[96:99]
	v_mfma_f32_16x16x32_bf16 v[96:99], v[68:71], v[166:169], v[100:103]
	v_mfma_f32_16x16x32_bf16 v[132:135], v[84:87], v[178:181], v[96:99]
	v_mfma_f32_16x16x32_bf16 v[96:99], v[68:71], v[182:185], v[128:131]
	v_mfma_f32_16x16x32_bf16 v[128:131], v[84:87], v[186:189], v[96:99]
	v_mfma_f32_16x16x32_bf16 v[96:99], v[68:71], v[190:193], v[116:119]
	v_mfma_f32_16x16x32_bf16 v[116:119], v[84:87], v[194:197], v[96:99]
	v_mfma_f32_16x16x32_bf16 v[96:99], v[68:71], v[198:201], v[108:111]
	v_mfma_f32_16x16x32_bf16 v[44:47], v[88:91], v[152:155], v[44:47]
	v_mfma_f32_16x16x32_bf16 v[36:39], v[88:91], v[166:169], v[36:39]
	v_mfma_f32_16x16x32_bf16 v[32:35], v[88:91], v[182:185], v[32:35]
	v_mfma_f32_16x16x32_bf16 v[20:23], v[88:91], v[190:193], v[20:23]
	v_mfma_f32_16x16x32_bf16 v[108:111], v[84:87], v[202:205], v[96:99]
	v_mfma_f32_16x16x32_bf16 v[12:15], v[88:91], v[198:201], v[12:15]
	v_mfma_f32_16x16x32_bf16 v[96:99], v[68:71], v[226:229], v[104:107]
	v_mfma_f32_16x16x32_bf16 v[8:11], v[88:91], v[226:229], v[8:11]
	v_mfma_f32_16x16x32_bf16 v[60:63], v[68:71], v[234:237], v[60:63]
	v_mfma_f32_16x16x32_bf16 v[0:3], v[88:91], v[234:237], v[0:3]
	v_mfma_f32_16x16x32_bf16 v[44:47], v[92:95], v[156:159], v[44:47]
	v_mfma_f32_16x16x32_bf16 v[36:39], v[92:95], v[178:181], v[36:39]
	v_mfma_f32_16x16x32_bf16 v[32:35], v[92:95], v[186:189], v[32:35]
	v_mfma_f32_16x16x32_bf16 v[20:23], v[92:95], v[194:197], v[20:23]
	v_mfma_f32_16x16x32_bf16 v[12:15], v[92:95], v[202:205], v[12:15]
	v_mfma_f32_16x16x32_bf16 v[104:107], v[84:87], v[230:233], v[96:99]
	v_mfma_f32_16x16x32_bf16 v[8:11], v[92:95], v[230:233], v[8:11]
	v_mfma_f32_16x16x32_bf16 v[60:63], v[84:87], v[238:241], v[60:63]
	v_mfma_f32_16x16x32_bf16 v[0:3], v[92:95], v[238:241], v[0:3]
	s_barrier
	s_add_i32 s69, s69, 2
	s_add_u32 vcc_hi, vcc_hi, 0x100
	s_addc_u32 s68, s68, 0
	s_cmp_gt_u32 s69, 13
	s_mov_b64 s[10:11], s[12:13]
	s_cbranch_scc0 .LBB0_1027
	s_and_b64 vcc, exec, s[90:91]
	s_cbranch_vccz .LBB0_1030
	s_barrier

;     __device__ __forceinline__ void operator()(f32x4 (&acc)[2][2][4][2], const Unit& u, int wr, int wc, int fr, int fq) const {
;     ...
;           if (wr == 0) { const float* sp = ssq + ((size_t)u.pm * 256 + t) * 16; const f32x4 a = *(const f32x4*)sp, b = *(const f32x4*)(sp + 4), c = *(const f32x4*)(sp + 8), d = *(const f32x4*)(sp + 12);
;               const f32x4 q = (a + b) + (c + d); rsL[t] = rsqrtf(((q[0] + q[1]) + (q[2] + q[3])) * (1.0f / 1024.0f) + EPS); }
.LBB0_1034:
	s_and_b64 vcc, exec, s[12:13]
	s_cbranch_vccz .LBB0_1036
	s_ashr_i32 s97, s96, 31
	s_lshl_b64 s[12:13], s[96:97], 14
	v_ashrrev_i32_e32 v69, 31, v68
	s_add_u32 s12, s18, s12
	s_addc_u32 s13, s19, s13
	v_lshlrev_b64 v[70:71], 6, v[68:69]
	v_lshl_add_u64 v[70:71], s[12:13], 0, v[70:71]
	s_waitcnt vmcnt(0)
	v_lshlrev_b32_e32 v69, 4, v84
	v_add_u32_e32 v69, v69, v188
	v_lshlrev_b32_e32 v69, 4, v69
	s_lshl_b32 s12, s59, 6
	v_add_u32_e32 v69, s12, v69
	v_add_u32_e32 v69, 0x23440, v69
	ds_read_b128 v[86:89], v69
	ds_read_b128 v[90:93], v69 offset:1024
	ds_read_b128 v[94:97], v69 offset:2048
	ds_read_b128 v[98:101], v69 offset:3072
	s_waitcnt lgkmcnt(0)
	v_lshl_add_u32 v68, v68, 2, 0
	v_add_u32_e32 v68, 0x22040, v68
	s_waitcnt vmcnt(2)
	v_pk_add_f32 v[70:71], v[88:89], v[92:93]
	v_pk_add_f32 v[86:87], v[86:87], v[90:91]
	s_waitcnt vmcnt(0)
	v_pk_add_f32 v[88:89], v[96:97], v[100:101]
	v_pk_add_f32 v[90:91], v[94:95], v[98:99]
	v_pk_add_f32 v[70:71], v[70:71], v[88:89]
	v_pk_add_f32 v[86:87], v[86:87], v[90:91]
	s_nop 0
	v_pk_mov_b32 v[88:89], v[86:87], v[70:71] op_sel:[1,0]
	v_mov_b32_e32 v87, v71
	v_pk_add_f32 v[70:71], v[88:89], v[86:87]
	s_nop 0
	v_add_f32_e32 v69, v70, v71
	v_fmamk_f32 v69, v69, 0x3a800000, v208
	v_mul_f32_e32 v70, 0x4b800000, v69
	v_cmp_gt_f32_e32 vcc, s44, v69
	s_nop 1
	v_cndmask_b32_e32 v69, v69, v70, vcc
	v_rsq_f32_e32 v69, v69
	s_nop 0
	v_mul_f32_e32 v70, 0x45800000, v69
	v_cndmask_b32_e32 v69, v69, v70, vcc
	ds_write_b32 v68, v69

; #define LAS __attribute__((address_space(3)))
; __global__ void __launch_bounds__(512, 2) mega(P parg) {
;     extern __shared__ __attribute__((aligned(16))) unsigned char lds_raw[];
;     LAS unsigned char* lds = (LAS unsigned char*)lds_raw;
	.amdhsa_kernel _Z4mega1P
		.amdhsa_group_segment_fixed_size 16384
		.amdhsa_private_segment_fixed_size 0
		.amdhsa_kernarg_size 496
		.amdhsa_user_sgpr_count 2
		.amdhsa_user_sgpr_dispatch_ptr 0
		.amdhsa_user_sgpr_queue_ptr 0
		.amdhsa_user_sgpr_kernarg_segment_ptr 1
		.amdhsa_user_sgpr_dispatch_id 0
		.amdhsa_user_sgpr_kernarg_preload_length 0
		.amdhsa_user_sgpr_kernarg_preload_offset 0
		.amdhsa_user_sgpr_private_segment_size 0
		.amdhsa_uses_dynamic_stack 0
		.amdhsa_enable_private_segment 0
		.amdhsa_system_sgpr_workgroup_id_x 1
		.amdhsa_system_sgpr_workgroup_id_y 0
		.amdhsa_system_sgpr_workgroup_id_z 0
		.amdhsa_system_sgpr_workgroup_info 0
		.amdhsa_system_vgpr_workitem_id 2
		.amdhsa_next_free_vgpr 256
		.amdhsa_next_free_sgpr 100
		.amdhsa_accum_offset 256
		.amdhsa_reserve_vcc 1
		.amdhsa_float_round_mode_32 0
		.amdhsa_float_round_mode_16_64 0
		.amdhsa_float_denorm_mode_32 3
		.amdhsa_float_denorm_mode_16_64 3
		.amdhsa_dx10_clamp 1
		.amdhsa_ieee_mode 1
		.amdhsa_fp16_overflow 0
		.amdhsa_tg_split 0
		.amdhsa_exception_fp_ieee_invalid_op 0
		.amdhsa_exception_fp_denorm_src 0
		.amdhsa_exception_fp_ieee_div_zero 0
		.amdhsa_exception_fp_ieee_overflow 0
		.amdhsa_exception_fp_ieee_underflow 0
		.amdhsa_exception_fp_ieee_inexact 0
		.amdhsa_exception_int_div_zero 0
	.end_amdhsa_kernel

; #define LAS __attribute__((address_space(3)))
; __global__ void __launch_bounds__(512, 2) mega(P parg) {
;     extern __shared__ __attribute__((aligned(16))) unsigned char lds_raw[];
;     LAS unsigned char* lds = (LAS unsigned char*)lds_raw;
amdhsa.kernels:
  - .agpr_count:     0
    .args:
      - .offset:         0
        .size:           240
        .value_kind:     by_value
      - .offset:         240
        .size:           4
        .value_kind:     hidden_block_count_x
      - .offset:         244
        .size:           4
        .value_kind:     hidden_block_count_y
      - .offset:         248
        .size:           4
        .value_kind:     hidden_block_count_z
      - .offset:         252
        .size:           2
        .value_kind:     hidden_group_size_x
      - .offset:         254
        .size:           2
        .value_kind:     hidden_group_size_y
      - .offset:         256
        .size:           2
        .value_kind:     hidden_group_size_z
      - .offset:         258
        .size:           2
        .value_kind:     hidden_remainder_x
      - .offset:         260
        .size:           2
        .value_kind:     hidden_remainder_y
      - .offset:         262
        .size:           2
        .value_kind:     hidden_remainder_z
      - .offset:         280
        .size:           8
        .value_kind:     hidden_global_offset_x
      - .offset:         288
        .size:           8
        .value_kind:     hidden_global_offset_y
      - .offset:         296
        .size:           8
        .value_kind:     hidden_global_offset_z
      - .offset:         304
        .size:           2
        .value_kind:     hidden_grid_dims
      - .offset:         328
        .size:           8
        .value_kind:     hidden_multigrid_sync_arg
      - .offset:         360
        .size:           4
        .value_kind:     hidden_dynamic_lds_size
    .group_segment_fixed_size: 16384
    .kernarg_segment_align: 8
    .kernarg_segment_size: 496
    .language:       OpenCL C
    .language_version:
      - 2
      - 0
    .max_flat_workgroup_size: 512
    .name:           _Z4mega1P
    .private_segment_fixed_size: 0
    .sgpr_count:     106
    .sgpr_spill_count: 240
    .symbol:         _Z4mega1P.kd
    .uniform_work_group_size: 1
    .uses_dynamic_stack: false
    .vgpr_count:     256
    .vgpr_spill_count: 0
    .wavefront_size: 64
